# comboB + P4 (GLU) epilogue loads software-pipelined (16 in flight)
# speedup vs baseline: 1.0584x; 1.0063x over previous
.LBB0_667:
	v_lshl_or_b32 v152, s33, 8, v165
	v_ashrrev_i32_e32 v153, 31, v152
	v_lshl_add_u64 v[154:155], v[152:153], 2, s[50:51]
	global_load_dwordx4 v[110:113], v[154:155], off
	global_load_dwordx4 v[106:109], v[154:155], off offset:16
	global_load_dwordx4 v[170:173], v[154:155], off offset:512
	global_load_dwordx4 v[174:177], v[154:155], off offset:528
	v_lshl_add_u32 v162, s36, 8, v1
	v_ashrrev_i32_e32 v163, 31, v162
	v_lshlrev_b64 v[156:157], 1, v[152:153]
	v_lshlrev_b64 v[158:159], 10, v[162:163]
	v_lshl_add_u64 v[158:159], v[158:159], 0, v[156:157]
	v_lshlrev_b64 v[160:161], 11, v[162:163]
	v_lshl_add_u64 v[160:161], v[160:161], 0, v[156:157]
	v_lshl_add_u64 v[160:161], s[8:9], 0, v[160:161]
	v_lshl_add_u64 v[152:153], s[0:1], 0, v[158:159]
	v_lshl_add_u64 v[154:155], s[6:7], 0, v[158:159]
	v_mov_b32_e32 v162, v152
	v_mov_b32_e32 v163, v153
	v_mov_b32_e32 v184, v154
	v_mov_b32_e32 v185, v155
	v_mov_b32_e32 v182, v160
	v_mov_b32_e32 v183, v161
	v_mov_b32_e32 v156, 0x4000
	v_mov_b32_e32 v157, 0
	v_mov_b32_e32 v158, 0x14000
	v_mov_b32_e32 v159, 0
	v_mov_b32_e32 v178, 0x8000
	v_mov_b32_e32 v179, 0
	v_mov_b32_e32 v180, 0x28000
	v_mov_b32_e32 v181, 0
	s_andn2_b64 vcc, exec, s[26:27]
	s_mov_b64 s[26:27], -1
	global_load_dwordx4 v[186:189], v[152:153], off nt
	global_load_dwordx4 v[190:193], v[154:155], off nt
	v_lshl_add_u64 v[152:153], v[152:153], 0, v[156:157]
	v_lshl_add_u64 v[154:155], v[154:155], 0, v[156:157]
	global_load_dwordx4 v[194:197], v[152:153], off nt
	global_load_dwordx4 v[198:201], v[154:155], off nt
	v_lshl_add_u64 v[152:153], v[152:153], 0, v[156:157]
	v_lshl_add_u64 v[154:155], v[154:155], 0, v[156:157]
	global_load_dwordx4 v[202:205], v[152:153], off nt
	global_load_dwordx4 v[206:209], v[154:155], off nt
	v_lshl_add_u64 v[152:153], v[152:153], 0, v[156:157]
	v_lshl_add_u64 v[154:155], v[154:155], 0, v[156:157]
	global_load_dwordx4 v[210:213], v[152:153], off nt
	global_load_dwordx4 v[214:217], v[154:155], off nt
	v_lshl_add_u64 v[152:153], v[152:153], 0, v[158:159]
	v_lshl_add_u64 v[154:155], v[154:155], 0, v[158:159]
	global_load_dwordx4 v[218:221], v[152:153], off nt
	global_load_dwordx4 v[222:225], v[154:155], off nt
	v_lshl_add_u64 v[152:153], v[152:153], 0, v[156:157]
	v_lshl_add_u64 v[154:155], v[154:155], 0, v[156:157]
	global_load_dwordx4 v[226:229], v[152:153], off nt
	global_load_dwordx4 v[230:233], v[154:155], off nt
	v_lshl_add_u64 v[152:153], v[152:153], 0, v[156:157]
	v_lshl_add_u64 v[154:155], v[154:155], 0, v[156:157]
	global_load_dwordx4 v[234:237], v[152:153], off nt
	global_load_dwordx4 v[238:241], v[154:155], off nt
	v_lshl_add_u64 v[152:153], v[152:153], 0, v[156:157]
	v_lshl_add_u64 v[154:155], v[154:155], 0, v[156:157]
	global_load_dwordx4 v[242:245], v[152:153], off nt
	global_load_dwordx4 v[246:249], v[154:155], off nt
	s_waitcnt vmcnt(16)
	v_add_f32_e32 v134, v134, v110
	v_add_f32_e32 v135, v135, v111
	v_add_f32_e32 v136, v136, v112
	v_add_f32_e32 v137, v137, v113
	v_add_f32_e32 v130, v130, v106
	v_add_f32_e32 v131, v131, v107
	v_add_f32_e32 v132, v132, v108
	v_add_f32_e32 v133, v133, v109
	v_mul_f32_e32 v134, 0xbfb8aa3b, v134
	v_mul_f32_e32 v135, 0xbfb8aa3b, v135
	v_mul_f32_e32 v136, 0xbfb8aa3b, v136
	v_mul_f32_e32 v137, 0xbfb8aa3b, v137
	v_mul_f32_e32 v130, 0xbfb8aa3b, v130
	v_mul_f32_e32 v131, 0xbfb8aa3b, v131
	v_mul_f32_e32 v132, 0xbfb8aa3b, v132
	v_mul_f32_e32 v133, 0xbfb8aa3b, v133
	v_exp_f32_e32 v134, v134
	v_exp_f32_e32 v135, v135
	v_exp_f32_e32 v136, v136
	v_exp_f32_e32 v137, v137
	v_exp_f32_e32 v130, v130
	v_exp_f32_e32 v131, v131
	v_exp_f32_e32 v132, v132
	v_exp_f32_e32 v133, v133
	v_add_f32_e32 v134, 1.0, v134
	v_add_f32_e32 v135, 1.0, v135
	v_add_f32_e32 v136, 1.0, v136
	v_add_f32_e32 v137, 1.0, v137
	v_add_f32_e32 v130, 1.0, v130
	v_add_f32_e32 v131, 1.0, v131
	v_add_f32_e32 v132, 1.0, v132
	v_add_f32_e32 v133, 1.0, v133
	v_rcp_f32_e32 v134, v134
	v_rcp_f32_e32 v135, v135
	v_rcp_f32_e32 v136, v136
	v_rcp_f32_e32 v137, v137
	v_rcp_f32_e32 v130, v130
	v_rcp_f32_e32 v131, v131
	v_rcp_f32_e32 v132, v132
	v_rcp_f32_e32 v133, v133
	s_waitcnt vmcnt(14)
	v_lshlrev_b32_e32 v146, 16, v186
	v_and_b32_e32 v147, 0xffff0000, v186
	v_lshlrev_b32_e32 v148, 16, v187
	v_and_b32_e32 v149, 0xffff0000, v187
	v_lshlrev_b32_e32 v150, 16, v188
	v_and_b32_e32 v151, 0xffff0000, v188
	v_lshlrev_b32_e32 v166, 16, v189
	v_and_b32_e32 v167, 0xffff0000, v189
	v_mul_f32_e32 v134, v134, v146
	v_mul_f32_e32 v135, v135, v147
	v_mul_f32_e32 v136, v136, v148
	v_mul_f32_e32 v137, v137, v149
	v_mul_f32_e32 v130, v130, v150
	v_mul_f32_e32 v131, v131, v151
	v_mul_f32_e32 v132, v132, v166
	v_mul_f32_e32 v133, v133, v167
	v_lshlrev_b32_e32 v146, 16, v190
	v_and_b32_e32 v147, 0xffff0000, v190
	v_lshlrev_b32_e32 v148, 16, v191
	v_and_b32_e32 v149, 0xffff0000, v191
	v_lshlrev_b32_e32 v150, 16, v192
	v_and_b32_e32 v151, 0xffff0000, v192
	v_lshlrev_b32_e32 v166, 16, v193
	v_and_b32_e32 v167, 0xffff0000, v193
	v_mul_f32_e32 v134, v134, v146
	v_mul_f32_e32 v135, v135, v147
	v_mul_f32_e32 v136, v136, v148
	v_mul_f32_e32 v137, v137, v149
	v_mul_f32_e32 v130, v130, v150
	v_mul_f32_e32 v131, v131, v151
	v_mul_f32_e32 v132, v132, v166
	v_mul_f32_e32 v133, v133, v167
	v_cvt_pk_bf16_f32 v138, v134, v135
	v_cvt_pk_bf16_f32 v139, v136, v137
	v_cvt_pk_bf16_f32 v140, v130, v131
	v_cvt_pk_bf16_f32 v141, v132, v133
	global_store_dwordx4 v[160:161], v[138:141], off offset:1024
	v_lshl_add_u64 v[160:161], v[160:161], 0, v[178:179]
	global_load_dwordx4 v[186:189], v[162:163], off offset:256 nt
	global_load_dwordx4 v[190:193], v[184:185], off offset:256 nt
	v_lshl_add_u64 v[162:163], v[162:163], 0, v[156:157]
	v_lshl_add_u64 v[184:185], v[184:185], 0, v[156:157]
	v_add_f32_e32 v126, v126, v110
	v_add_f32_e32 v127, v127, v111
	v_add_f32_e32 v128, v128, v112
	v_add_f32_e32 v129, v129, v113
	v_add_f32_e32 v122, v122, v106
	v_add_f32_e32 v123, v123, v107
	v_add_f32_e32 v124, v124, v108
	v_add_f32_e32 v125, v125, v109
	v_mul_f32_e32 v126, 0xbfb8aa3b, v126
	v_mul_f32_e32 v127, 0xbfb8aa3b, v127
	v_mul_f32_e32 v128, 0xbfb8aa3b, v128
	v_mul_f32_e32 v129, 0xbfb8aa3b, v129
	v_mul_f32_e32 v122, 0xbfb8aa3b, v122
	v_mul_f32_e32 v123, 0xbfb8aa3b, v123
	v_mul_f32_e32 v124, 0xbfb8aa3b, v124
	v_mul_f32_e32 v125, 0xbfb8aa3b, v125
	v_exp_f32_e32 v126, v126
	v_exp_f32_e32 v127, v127
	v_exp_f32_e32 v128, v128
	v_exp_f32_e32 v129, v129
	v_exp_f32_e32 v122, v122
	v_exp_f32_e32 v123, v123
	v_exp_f32_e32 v124, v124
	v_exp_f32_e32 v125, v125
	v_add_f32_e32 v126, 1.0, v126
	v_add_f32_e32 v127, 1.0, v127
	v_add_f32_e32 v128, 1.0, v128
	v_add_f32_e32 v129, 1.0, v129
	v_add_f32_e32 v122, 1.0, v122
	v_add_f32_e32 v123, 1.0, v123
	v_add_f32_e32 v124, 1.0, v124
	v_add_f32_e32 v125, 1.0, v125
	v_rcp_f32_e32 v126, v126
	v_rcp_f32_e32 v127, v127
	v_rcp_f32_e32 v128, v128
	v_rcp_f32_e32 v129, v129
	v_rcp_f32_e32 v122, v122
	v_rcp_f32_e32 v123, v123
	v_rcp_f32_e32 v124, v124
	v_rcp_f32_e32 v125, v125
	s_waitcnt vmcnt(15)
	v_lshlrev_b32_e32 v146, 16, v194
	v_and_b32_e32 v147, 0xffff0000, v194
	v_lshlrev_b32_e32 v148, 16, v195
	v_and_b32_e32 v149, 0xffff0000, v195
	v_lshlrev_b32_e32 v150, 16, v196
	v_and_b32_e32 v151, 0xffff0000, v196
	v_lshlrev_b32_e32 v166, 16, v197
	v_and_b32_e32 v167, 0xffff0000, v197
	v_mul_f32_e32 v126, v126, v146
	v_mul_f32_e32 v127, v127, v147
	v_mul_f32_e32 v128, v128, v148
	v_mul_f32_e32 v129, v129, v149
	v_mul_f32_e32 v122, v122, v150
	v_mul_f32_e32 v123, v123, v151
	v_mul_f32_e32 v124, v124, v166
	v_mul_f32_e32 v125, v125, v167
	v_lshlrev_b32_e32 v146, 16, v198
	v_and_b32_e32 v147, 0xffff0000, v198
	v_lshlrev_b32_e32 v148, 16, v199
	v_and_b32_e32 v149, 0xffff0000, v199
	v_lshlrev_b32_e32 v150, 16, v200
	v_and_b32_e32 v151, 0xffff0000, v200
	v_lshlrev_b32_e32 v166, 16, v201
	v_and_b32_e32 v167, 0xffff0000, v201
	v_mul_f32_e32 v126, v126, v146
	v_mul_f32_e32 v127, v127, v147
	v_mul_f32_e32 v128, v128, v148
	v_mul_f32_e32 v129, v129, v149
	v_mul_f32_e32 v122, v122, v150
	v_mul_f32_e32 v123, v123, v151
	v_mul_f32_e32 v124, v124, v166
	v_mul_f32_e32 v125, v125, v167
	v_cvt_pk_bf16_f32 v142, v126, v127
	v_cvt_pk_bf16_f32 v143, v128, v129
	v_cvt_pk_bf16_f32 v144, v122, v123
	v_cvt_pk_bf16_f32 v145, v124, v125
	global_store_dwordx4 v[160:161], v[142:145], off offset:1024
	v_lshl_add_u64 v[160:161], v[160:161], 0, v[178:179]
	global_load_dwordx4 v[194:197], v[162:163], off offset:256 nt
	global_load_dwordx4 v[198:201], v[184:185], off offset:256 nt
	v_lshl_add_u64 v[162:163], v[162:163], 0, v[156:157]
	v_lshl_add_u64 v[184:185], v[184:185], 0, v[156:157]
	v_add_f32_e32 v118, v118, v110
	v_add_f32_e32 v119, v119, v111
	v_add_f32_e32 v120, v120, v112
	v_add_f32_e32 v121, v121, v113
	v_add_f32_e32 v114, v114, v106
	v_add_f32_e32 v115, v115, v107
	v_add_f32_e32 v116, v116, v108
	v_add_f32_e32 v117, v117, v109
	v_mul_f32_e32 v118, 0xbfb8aa3b, v118
	v_mul_f32_e32 v119, 0xbfb8aa3b, v119
	v_mul_f32_e32 v120, 0xbfb8aa3b, v120
	v_mul_f32_e32 v121, 0xbfb8aa3b, v121
	v_mul_f32_e32 v114, 0xbfb8aa3b, v114
	v_mul_f32_e32 v115, 0xbfb8aa3b, v115
	v_mul_f32_e32 v116, 0xbfb8aa3b, v116
	v_mul_f32_e32 v117, 0xbfb8aa3b, v117
	v_exp_f32_e32 v118, v118
	v_exp_f32_e32 v119, v119
	v_exp_f32_e32 v120, v120
	v_exp_f32_e32 v121, v121
	v_exp_f32_e32 v114, v114
	v_exp_f32_e32 v115, v115
	v_exp_f32_e32 v116, v116
	v_exp_f32_e32 v117, v117
	v_add_f32_e32 v118, 1.0, v118
	v_add_f32_e32 v119, 1.0, v119
	v_add_f32_e32 v120, 1.0, v120
	v_add_f32_e32 v121, 1.0, v121
	v_add_f32_e32 v114, 1.0, v114
	v_add_f32_e32 v115, 1.0, v115
	v_add_f32_e32 v116, 1.0, v116
	v_add_f32_e32 v117, 1.0, v117
	v_rcp_f32_e32 v118, v118
	v_rcp_f32_e32 v119, v119
	v_rcp_f32_e32 v120, v120
	v_rcp_f32_e32 v121, v121
	v_rcp_f32_e32 v114, v114
	v_rcp_f32_e32 v115, v115
	v_rcp_f32_e32 v116, v116
	v_rcp_f32_e32 v117, v117
	s_waitcnt vmcnt(16)
	v_lshlrev_b32_e32 v146, 16, v202
	v_and_b32_e32 v147, 0xffff0000, v202
	v_lshlrev_b32_e32 v148, 16, v203
	v_and_b32_e32 v149, 0xffff0000, v203
	v_lshlrev_b32_e32 v150, 16, v204
	v_and_b32_e32 v151, 0xffff0000, v204
	v_lshlrev_b32_e32 v166, 16, v205
	v_and_b32_e32 v167, 0xffff0000, v205
	v_mul_f32_e32 v118, v118, v146
	v_mul_f32_e32 v119, v119, v147
	v_mul_f32_e32 v120, v120, v148
	v_mul_f32_e32 v121, v121, v149
	v_mul_f32_e32 v114, v114, v150
	v_mul_f32_e32 v115, v115, v151
	v_mul_f32_e32 v116, v116, v166
	v_mul_f32_e32 v117, v117, v167
	v_lshlrev_b32_e32 v146, 16, v206
	v_and_b32_e32 v147, 0xffff0000, v206
	v_lshlrev_b32_e32 v148, 16, v207
	v_and_b32_e32 v149, 0xffff0000, v207
	v_lshlrev_b32_e32 v150, 16, v208
	v_and_b32_e32 v151, 0xffff0000, v208
	v_lshlrev_b32_e32 v166, 16, v209
	v_and_b32_e32 v167, 0xffff0000, v209
	v_mul_f32_e32 v118, v118, v146
	v_mul_f32_e32 v119, v119, v147
	v_mul_f32_e32 v120, v120, v148
	v_mul_f32_e32 v121, v121, v149
	v_mul_f32_e32 v114, v114, v150
	v_mul_f32_e32 v115, v115, v151
	v_mul_f32_e32 v116, v116, v166
	v_mul_f32_e32 v117, v117, v167
	v_cvt_pk_bf16_f32 v138, v118, v119
	v_cvt_pk_bf16_f32 v139, v120, v121
	v_cvt_pk_bf16_f32 v140, v114, v115
	v_cvt_pk_bf16_f32 v141, v116, v117
	global_store_dwordx4 v[160:161], v[138:141], off offset:1024
	v_lshl_add_u64 v[160:161], v[160:161], 0, v[178:179]
	global_load_dwordx4 v[202:205], v[162:163], off offset:256 nt
	global_load_dwordx4 v[206:209], v[184:185], off offset:256 nt
	v_lshl_add_u64 v[162:163], v[162:163], 0, v[156:157]
	v_lshl_add_u64 v[184:185], v[184:185], 0, v[156:157]
	v_add_f32_e32 v102, v102, v110
	v_add_f32_e32 v103, v103, v111
	v_add_f32_e32 v104, v104, v112
	v_add_f32_e32 v105, v105, v113
	v_add_f32_e32 v98, v98, v106
	v_add_f32_e32 v99, v99, v107
	v_add_f32_e32 v100, v100, v108
	v_add_f32_e32 v101, v101, v109
	v_mul_f32_e32 v102, 0xbfb8aa3b, v102
	v_mul_f32_e32 v103, 0xbfb8aa3b, v103
	v_mul_f32_e32 v104, 0xbfb8aa3b, v104
	v_mul_f32_e32 v105, 0xbfb8aa3b, v105
	v_mul_f32_e32 v98, 0xbfb8aa3b, v98
	v_mul_f32_e32 v99, 0xbfb8aa3b, v99
	v_mul_f32_e32 v100, 0xbfb8aa3b, v100
	v_mul_f32_e32 v101, 0xbfb8aa3b, v101
	v_exp_f32_e32 v102, v102
	v_exp_f32_e32 v103, v103
	v_exp_f32_e32 v104, v104
	v_exp_f32_e32 v105, v105
	v_exp_f32_e32 v98, v98
	v_exp_f32_e32 v99, v99
	v_exp_f32_e32 v100, v100
	v_exp_f32_e32 v101, v101
	v_add_f32_e32 v102, 1.0, v102
	v_add_f32_e32 v103, 1.0, v103
	v_add_f32_e32 v104, 1.0, v104
	v_add_f32_e32 v105, 1.0, v105
	v_add_f32_e32 v98, 1.0, v98
	v_add_f32_e32 v99, 1.0, v99
	v_add_f32_e32 v100, 1.0, v100
	v_add_f32_e32 v101, 1.0, v101
	v_rcp_f32_e32 v102, v102
	v_rcp_f32_e32 v103, v103
	v_rcp_f32_e32 v104, v104
	v_rcp_f32_e32 v105, v105
	v_rcp_f32_e32 v98, v98
	v_rcp_f32_e32 v99, v99
	v_rcp_f32_e32 v100, v100
	v_rcp_f32_e32 v101, v101
	s_waitcnt vmcnt(17)
	v_lshlrev_b32_e32 v146, 16, v210
	v_and_b32_e32 v147, 0xffff0000, v210
	v_lshlrev_b32_e32 v148, 16, v211
	v_and_b32_e32 v149, 0xffff0000, v211
	v_lshlrev_b32_e32 v150, 16, v212
	v_and_b32_e32 v151, 0xffff0000, v212
	v_lshlrev_b32_e32 v166, 16, v213
	v_and_b32_e32 v167, 0xffff0000, v213
	v_mul_f32_e32 v102, v102, v146
	v_mul_f32_e32 v103, v103, v147
	v_mul_f32_e32 v104, v104, v148
	v_mul_f32_e32 v105, v105, v149
	v_mul_f32_e32 v98, v98, v150
	v_mul_f32_e32 v99, v99, v151
	v_mul_f32_e32 v100, v100, v166
	v_mul_f32_e32 v101, v101, v167
	v_lshlrev_b32_e32 v146, 16, v214
	v_and_b32_e32 v147, 0xffff0000, v214
	v_lshlrev_b32_e32 v148, 16, v215
	v_and_b32_e32 v149, 0xffff0000, v215
	v_lshlrev_b32_e32 v150, 16, v216
	v_and_b32_e32 v151, 0xffff0000, v216
	v_lshlrev_b32_e32 v166, 16, v217
	v_and_b32_e32 v167, 0xffff0000, v217
	v_mul_f32_e32 v102, v102, v146
	v_mul_f32_e32 v103, v103, v147
	v_mul_f32_e32 v104, v104, v148
	v_mul_f32_e32 v105, v105, v149
	v_mul_f32_e32 v98, v98, v150
	v_mul_f32_e32 v99, v99, v151
	v_mul_f32_e32 v100, v100, v166
	v_mul_f32_e32 v101, v101, v167
	v_cvt_pk_bf16_f32 v142, v102, v103
	v_cvt_pk_bf16_f32 v143, v104, v105
	v_cvt_pk_bf16_f32 v144, v98, v99
	v_cvt_pk_bf16_f32 v145, v100, v101
	global_store_dwordx4 v[160:161], v[142:145], off offset:1024
	v_lshl_add_u64 v[160:161], v[160:161], 0, v[180:181]
	global_load_dwordx4 v[210:213], v[162:163], off offset:256 nt
	global_load_dwordx4 v[214:217], v[184:185], off offset:256 nt
	v_lshl_add_u64 v[162:163], v[162:163], 0, v[158:159]
	v_lshl_add_u64 v[184:185], v[184:185], 0, v[158:159]
	v_add_f32_e32 v94, v94, v110
	v_add_f32_e32 v95, v95, v111
	v_add_f32_e32 v96, v96, v112
	v_add_f32_e32 v97, v97, v113
	v_add_f32_e32 v90, v90, v106
	v_add_f32_e32 v91, v91, v107
	v_add_f32_e32 v92, v92, v108
	v_add_f32_e32 v93, v93, v109
	v_mul_f32_e32 v94, 0xbfb8aa3b, v94
	v_mul_f32_e32 v95, 0xbfb8aa3b, v95
	v_mul_f32_e32 v96, 0xbfb8aa3b, v96
	v_mul_f32_e32 v97, 0xbfb8aa3b, v97
	v_mul_f32_e32 v90, 0xbfb8aa3b, v90
	v_mul_f32_e32 v91, 0xbfb8aa3b, v91
	v_mul_f32_e32 v92, 0xbfb8aa3b, v92
	v_mul_f32_e32 v93, 0xbfb8aa3b, v93
	v_exp_f32_e32 v94, v94
	v_exp_f32_e32 v95, v95
	v_exp_f32_e32 v96, v96
	v_exp_f32_e32 v97, v97
	v_exp_f32_e32 v90, v90
	v_exp_f32_e32 v91, v91
	v_exp_f32_e32 v92, v92
	v_exp_f32_e32 v93, v93
	v_add_f32_e32 v94, 1.0, v94
	v_add_f32_e32 v95, 1.0, v95
	v_add_f32_e32 v96, 1.0, v96
	v_add_f32_e32 v97, 1.0, v97
	v_add_f32_e32 v90, 1.0, v90
	v_add_f32_e32 v91, 1.0, v91
	v_add_f32_e32 v92, 1.0, v92
	v_add_f32_e32 v93, 1.0, v93
	v_rcp_f32_e32 v94, v94
	v_rcp_f32_e32 v95, v95
	v_rcp_f32_e32 v96, v96
	v_rcp_f32_e32 v97, v97
	v_rcp_f32_e32 v90, v90
	v_rcp_f32_e32 v91, v91
	v_rcp_f32_e32 v92, v92
	v_rcp_f32_e32 v93, v93
	s_waitcnt vmcnt(18)
	v_lshlrev_b32_e32 v146, 16, v218
	v_and_b32_e32 v147, 0xffff0000, v218
	v_lshlrev_b32_e32 v148, 16, v219
	v_and_b32_e32 v149, 0xffff0000, v219
	v_lshlrev_b32_e32 v150, 16, v220
	v_and_b32_e32 v151, 0xffff0000, v220
	v_lshlrev_b32_e32 v166, 16, v221
	v_and_b32_e32 v167, 0xffff0000, v221
	v_mul_f32_e32 v94, v94, v146
	v_mul_f32_e32 v95, v95, v147
	v_mul_f32_e32 v96, v96, v148
	v_mul_f32_e32 v97, v97, v149
	v_mul_f32_e32 v90, v90, v150
	v_mul_f32_e32 v91, v91, v151
	v_mul_f32_e32 v92, v92, v166
	v_mul_f32_e32 v93, v93, v167
	v_lshlrev_b32_e32 v146, 16, v222
	v_and_b32_e32 v147, 0xffff0000, v222
	v_lshlrev_b32_e32 v148, 16, v223
	v_and_b32_e32 v149, 0xffff0000, v223
	v_lshlrev_b32_e32 v150, 16, v224
	v_and_b32_e32 v151, 0xffff0000, v224
	v_lshlrev_b32_e32 v166, 16, v225
	v_and_b32_e32 v167, 0xffff0000, v225
	v_mul_f32_e32 v94, v94, v146
	v_mul_f32_e32 v95, v95, v147
	v_mul_f32_e32 v96, v96, v148
	v_mul_f32_e32 v97, v97, v149
	v_mul_f32_e32 v90, v90, v150
	v_mul_f32_e32 v91, v91, v151
	v_mul_f32_e32 v92, v92, v166
	v_mul_f32_e32 v93, v93, v167
	v_cvt_pk_bf16_f32 v138, v94, v95
	v_cvt_pk_bf16_f32 v139, v96, v97
	v_cvt_pk_bf16_f32 v140, v90, v91
	v_cvt_pk_bf16_f32 v141, v92, v93
	global_store_dwordx4 v[160:161], v[138:141], off offset:1024
	v_lshl_add_u64 v[160:161], v[160:161], 0, v[178:179]
	global_load_dwordx4 v[218:221], v[162:163], off offset:256 nt
	global_load_dwordx4 v[222:225], v[184:185], off offset:256 nt
	v_lshl_add_u64 v[162:163], v[162:163], 0, v[156:157]
	v_lshl_add_u64 v[184:185], v[184:185], 0, v[156:157]
	v_add_f32_e32 v86, v86, v110
	v_add_f32_e32 v87, v87, v111
	v_add_f32_e32 v88, v88, v112
	v_add_f32_e32 v89, v89, v113
	v_add_f32_e32 v82, v82, v106
	v_add_f32_e32 v83, v83, v107
	v_add_f32_e32 v84, v84, v108
	v_add_f32_e32 v85, v85, v109
	v_mul_f32_e32 v86, 0xbfb8aa3b, v86
	v_mul_f32_e32 v87, 0xbfb8aa3b, v87
	v_mul_f32_e32 v88, 0xbfb8aa3b, v88
	v_mul_f32_e32 v89, 0xbfb8aa3b, v89
	v_mul_f32_e32 v82, 0xbfb8aa3b, v82
	v_mul_f32_e32 v83, 0xbfb8aa3b, v83
	v_mul_f32_e32 v84, 0xbfb8aa3b, v84
	v_mul_f32_e32 v85, 0xbfb8aa3b, v85
	v_exp_f32_e32 v86, v86
	v_exp_f32_e32 v87, v87
	v_exp_f32_e32 v88, v88
	v_exp_f32_e32 v89, v89
	v_exp_f32_e32 v82, v82
	v_exp_f32_e32 v83, v83
	v_exp_f32_e32 v84, v84
	v_exp_f32_e32 v85, v85
	v_add_f32_e32 v86, 1.0, v86
	v_add_f32_e32 v87, 1.0, v87
	v_add_f32_e32 v88, 1.0, v88
	v_add_f32_e32 v89, 1.0, v89
	v_add_f32_e32 v82, 1.0, v82
	v_add_f32_e32 v83, 1.0, v83
	v_add_f32_e32 v84, 1.0, v84
	v_add_f32_e32 v85, 1.0, v85
	v_rcp_f32_e32 v86, v86
	v_rcp_f32_e32 v87, v87
	v_rcp_f32_e32 v88, v88
	v_rcp_f32_e32 v89, v89
	v_rcp_f32_e32 v82, v82
	v_rcp_f32_e32 v83, v83
	v_rcp_f32_e32 v84, v84
	v_rcp_f32_e32 v85, v85
	s_waitcnt vmcnt(19)
; __device__ __forceinline__ unsigned cvt_pk_bf16(float lo, float hi) { unsigned r; asm volatile("v_cvt_pk_bf16_f32 %0, %1, %2" : "=v"(r) : "v"(lo), "v"(hi)); return r; }
; __device__ __forceinline__ float bflo(unsigned w) { return __uint_as_float(w << 16); }
; __device__ __forceinline__ float bfhi(unsigned w) { return __uint_as_float(w & 0xffff0000u); }
; __device__ __forceinline__ float sigm(float v) { return frcp(1.f + fexp2(-LOG2E * v)); }
;     __device__ __forceinline__ void operator()(const f32x4 (&acc)[2][2][4][2], const Unit& u, int wr, int wc, int fr, int fq) const { if (u.pn >= 9) g(acc, u, wr, wc, fr, fq); else a(acc, u, wr, wc, fr, fq); }
;     __device__ __forceinline__ void operator()(const f32x4 (&acc)[2][2][4][2], const Unit& u, int wr, int wc, int fr, int fq) const {
;         const int row0 = u.pm * 256 + wr * 64 + fr, c8 = wc * 32 + 8 * fq;
; #pragma unroll
;         for (int bj = 0; bj < 2; ++bj) {
;             const int col = u.pn * 256 + bj * 128 + c8;
;             const f32x4 b0 = *(const f32x4*)(b_glu + col), b1 = *(const f32x4*)(b_glu + col + 4);
; #pragma unroll
;             for (int ai = 0; ai < 2; ++ai)
; #pragma unroll
;                 for (int m = 0; m < 4; ++m) {
;                     const size_t row = (size_t)(row0 + ai * 128 + m * 16);
;                     const v4u y = __builtin_nontemporal_load((const v4u*)(YG + row * 512 + col)), z = __builtin_nontemporal_load((const v4u*)(ZS + row * 512 + col));
;                     const f32x4 a0 = acc[ai][bj][m][0], a1 = acc[ai][bj][m][1];
;                     v4u w;
;                     w.x = pg8::cvt_pk_bf16(bflo(y.x) * sigm(a0[0] + b0[0]) * bflo(z.x), bfhi(y.x) * sigm(a0[1] + b0[1]) * bfhi(z.x));
;                     w.y = pg8::cvt_pk_bf16(bflo(y.y) * sigm(a0[2] + b0[2]) * bflo(z.y), bfhi(y.y) * sigm(a0[3] + b0[3]) * bfhi(z.y));
;                     w.z = pg8::cvt_pk_bf16(bflo(y.z) * sigm(a1[0] + b1[0]) * bflo(z.z), bfhi(y.z) * sigm(a1[1] + b1[1]) * bfhi(z.z));
;                     w.w = pg8::cvt_pk_bf16(bflo(y.w) * sigm(a1[2] + b1[2]) * bflo(z.w), bfhi(y.w) * sigm(a1[3] + b1[3]) * bfhi(z.w));
;                     *(v4u*)(A5 + row * 1024 + 512 + col) = w;
;                 }
;         }
;     }
	v_lshlrev_b32_e32 v146, 16, v226
	v_and_b32_e32 v147, 0xffff0000, v226
	v_lshlrev_b32_e32 v148, 16, v227
	v_and_b32_e32 v149, 0xffff0000, v227
	v_lshlrev_b32_e32 v150, 16, v228
	v_and_b32_e32 v151, 0xffff0000, v228
	v_lshlrev_b32_e32 v166, 16, v229
	v_and_b32_e32 v167, 0xffff0000, v229
	v_mul_f32_e32 v86, v86, v146
	v_mul_f32_e32 v87, v87, v147
	v_mul_f32_e32 v88, v88, v148
	v_mul_f32_e32 v89, v89, v149
	v_mul_f32_e32 v82, v82, v150
	v_mul_f32_e32 v83, v83, v151
	v_mul_f32_e32 v84, v84, v166
	v_mul_f32_e32 v85, v85, v167
	v_lshlrev_b32_e32 v146, 16, v230
	v_and_b32_e32 v147, 0xffff0000, v230
	v_lshlrev_b32_e32 v148, 16, v231
	v_and_b32_e32 v149, 0xffff0000, v231
	v_lshlrev_b32_e32 v150, 16, v232
	v_and_b32_e32 v151, 0xffff0000, v232
	v_lshlrev_b32_e32 v166, 16, v233
	v_and_b32_e32 v167, 0xffff0000, v233
	v_mul_f32_e32 v86, v86, v146
	v_mul_f32_e32 v87, v87, v147
	v_mul_f32_e32 v88, v88, v148
	v_mul_f32_e32 v89, v89, v149
	v_mul_f32_e32 v82, v82, v150
	v_mul_f32_e32 v83, v83, v151
	v_mul_f32_e32 v84, v84, v166
	v_mul_f32_e32 v85, v85, v167
	v_cvt_pk_bf16_f32 v142, v86, v87
	v_cvt_pk_bf16_f32 v143, v88, v89
	v_cvt_pk_bf16_f32 v144, v82, v83
	v_cvt_pk_bf16_f32 v145, v84, v85
	global_store_dwordx4 v[160:161], v[142:145], off offset:1024
	v_lshl_add_u64 v[160:161], v[160:161], 0, v[178:179]
	global_load_dwordx4 v[226:229], v[162:163], off offset:256 nt
	global_load_dwordx4 v[230:233], v[184:185], off offset:256 nt
	v_lshl_add_u64 v[162:163], v[162:163], 0, v[156:157]
	v_lshl_add_u64 v[184:185], v[184:185], 0, v[156:157]
	v_add_f32_e32 v78, v78, v110
	v_add_f32_e32 v79, v79, v111
	v_add_f32_e32 v80, v80, v112
	v_add_f32_e32 v81, v81, v113
	v_add_f32_e32 v74, v74, v106
	v_add_f32_e32 v75, v75, v107
	v_add_f32_e32 v76, v76, v108
	v_add_f32_e32 v77, v77, v109
	v_mul_f32_e32 v78, 0xbfb8aa3b, v78
	v_mul_f32_e32 v79, 0xbfb8aa3b, v79
	v_mul_f32_e32 v80, 0xbfb8aa3b, v80
	v_mul_f32_e32 v81, 0xbfb8aa3b, v81
	v_mul_f32_e32 v74, 0xbfb8aa3b, v74
	v_mul_f32_e32 v75, 0xbfb8aa3b, v75
	v_mul_f32_e32 v76, 0xbfb8aa3b, v76
	v_mul_f32_e32 v77, 0xbfb8aa3b, v77
	v_exp_f32_e32 v78, v78
	v_exp_f32_e32 v79, v79
	v_exp_f32_e32 v80, v80
	v_exp_f32_e32 v81, v81
	v_exp_f32_e32 v74, v74
	v_exp_f32_e32 v75, v75
	v_exp_f32_e32 v76, v76
	v_exp_f32_e32 v77, v77
	v_add_f32_e32 v78, 1.0, v78
	v_add_f32_e32 v79, 1.0, v79
	v_add_f32_e32 v80, 1.0, v80
	v_add_f32_e32 v81, 1.0, v81
	v_add_f32_e32 v74, 1.0, v74
	v_add_f32_e32 v75, 1.0, v75
	v_add_f32_e32 v76, 1.0, v76
	v_add_f32_e32 v77, 1.0, v77
	v_rcp_f32_e32 v78, v78
	v_rcp_f32_e32 v79, v79
	v_rcp_f32_e32 v80, v80
	v_rcp_f32_e32 v81, v81
	v_rcp_f32_e32 v74, v74
	v_rcp_f32_e32 v75, v75
	v_rcp_f32_e32 v76, v76
	v_rcp_f32_e32 v77, v77
	s_waitcnt vmcnt(20)
	v_lshlrev_b32_e32 v146, 16, v234
	v_and_b32_e32 v147, 0xffff0000, v234
	v_lshlrev_b32_e32 v148, 16, v235
	v_and_b32_e32 v149, 0xffff0000, v235
	v_lshlrev_b32_e32 v150, 16, v236
	v_and_b32_e32 v151, 0xffff0000, v236
	v_lshlrev_b32_e32 v166, 16, v237
	v_and_b32_e32 v167, 0xffff0000, v237
	v_mul_f32_e32 v78, v78, v146
	v_mul_f32_e32 v79, v79, v147
	v_mul_f32_e32 v80, v80, v148
	v_mul_f32_e32 v81, v81, v149
	v_mul_f32_e32 v74, v74, v150
	v_mul_f32_e32 v75, v75, v151
	v_mul_f32_e32 v76, v76, v166
	v_mul_f32_e32 v77, v77, v167
	v_lshlrev_b32_e32 v146, 16, v238
	v_and_b32_e32 v147, 0xffff0000, v238
	v_lshlrev_b32_e32 v148, 16, v239
	v_and_b32_e32 v149, 0xffff0000, v239
	v_lshlrev_b32_e32 v150, 16, v240
	v_and_b32_e32 v151, 0xffff0000, v240
	v_lshlrev_b32_e32 v166, 16, v241
	v_and_b32_e32 v167, 0xffff0000, v241
	v_mul_f32_e32 v78, v78, v146
	v_mul_f32_e32 v79, v79, v147
	v_mul_f32_e32 v80, v80, v148
	v_mul_f32_e32 v81, v81, v149
	v_mul_f32_e32 v74, v74, v150
	v_mul_f32_e32 v75, v75, v151
	v_mul_f32_e32 v76, v76, v166
	v_mul_f32_e32 v77, v77, v167
	v_cvt_pk_bf16_f32 v138, v78, v79
	v_cvt_pk_bf16_f32 v139, v80, v81
	v_cvt_pk_bf16_f32 v140, v74, v75
	v_cvt_pk_bf16_f32 v141, v76, v77
	global_store_dwordx4 v[160:161], v[138:141], off offset:1024
	v_lshl_add_u64 v[160:161], v[160:161], 0, v[178:179]
	global_load_dwordx4 v[234:237], v[162:163], off offset:256 nt
	global_load_dwordx4 v[238:241], v[184:185], off offset:256 nt
	v_lshl_add_u64 v[162:163], v[162:163], 0, v[156:157]
	v_lshl_add_u64 v[184:185], v[184:185], 0, v[156:157]
	v_add_f32_e32 v70, v70, v110
	v_add_f32_e32 v71, v71, v111
	v_add_f32_e32 v72, v72, v112
	v_add_f32_e32 v73, v73, v113
	v_add_f32_e32 v66, v66, v106
	v_add_f32_e32 v67, v67, v107
	v_add_f32_e32 v68, v68, v108
	v_add_f32_e32 v69, v69, v109
	v_mul_f32_e32 v70, 0xbfb8aa3b, v70
	v_mul_f32_e32 v71, 0xbfb8aa3b, v71
	v_mul_f32_e32 v72, 0xbfb8aa3b, v72
	v_mul_f32_e32 v73, 0xbfb8aa3b, v73
	v_mul_f32_e32 v66, 0xbfb8aa3b, v66
	v_mul_f32_e32 v67, 0xbfb8aa3b, v67
	v_mul_f32_e32 v68, 0xbfb8aa3b, v68
	v_mul_f32_e32 v69, 0xbfb8aa3b, v69
	v_exp_f32_e32 v70, v70
	v_exp_f32_e32 v71, v71
	v_exp_f32_e32 v72, v72
	v_exp_f32_e32 v73, v73
	v_exp_f32_e32 v66, v66
	v_exp_f32_e32 v67, v67
	v_exp_f32_e32 v68, v68
	v_exp_f32_e32 v69, v69
	v_add_f32_e32 v70, 1.0, v70
	v_add_f32_e32 v71, 1.0, v71
	v_add_f32_e32 v72, 1.0, v72
	v_add_f32_e32 v73, 1.0, v73
	v_add_f32_e32 v66, 1.0, v66
	v_add_f32_e32 v67, 1.0, v67
	v_add_f32_e32 v68, 1.0, v68
	v_add_f32_e32 v69, 1.0, v69
	v_rcp_f32_e32 v70, v70
	v_rcp_f32_e32 v71, v71
	v_rcp_f32_e32 v72, v72
	v_rcp_f32_e32 v73, v73
	v_rcp_f32_e32 v66, v66
	v_rcp_f32_e32 v67, v67
	v_rcp_f32_e32 v68, v68
	v_rcp_f32_e32 v69, v69
	s_waitcnt vmcnt(21)
; __device__ __forceinline__ unsigned cvt_pk_bf16(float lo, float hi) { unsigned r; asm volatile("v_cvt_pk_bf16_f32 %0, %1, %2" : "=v"(r) : "v"(lo), "v"(hi)); return r; }
; __device__ __forceinline__ float bflo(unsigned w) { return __uint_as_float(w << 16); }
; __device__ __forceinline__ float bfhi(unsigned w) { return __uint_as_float(w & 0xffff0000u); }
; __device__ __forceinline__ float sigm(float v) { return frcp(1.f + fexp2(-LOG2E * v)); }
;     __device__ __forceinline__ void operator()(const f32x4 (&acc)[2][2][4][2], const Unit& u, int wr, int wc, int fr, int fq) const { if (u.pn >= 9) g(acc, u, wr, wc, fr, fq); else a(acc, u, wr, wc, fr, fq); }
;     __device__ __forceinline__ void operator()(const f32x4 (&acc)[2][2][4][2], const Unit& u, int wr, int wc, int fr, int fq) const {
;         const int row0 = u.pm * 256 + wr * 64 + fr, c8 = wc * 32 + 8 * fq;
; #pragma unroll
;         for (int bj = 0; bj < 2; ++bj) {
;             const int col = u.pn * 256 + bj * 128 + c8;
;             const f32x4 b0 = *(const f32x4*)(b_glu + col), b1 = *(const f32x4*)(b_glu + col + 4);
; #pragma unroll
;             for (int ai = 0; ai < 2; ++ai)
; #pragma unroll
;                 for (int m = 0; m < 4; ++m) {
;                     const size_t row = (size_t)(row0 + ai * 128 + m * 16);
;                     const v4u y = __builtin_nontemporal_load((const v4u*)(YG + row * 512 + col)), z = __builtin_nontemporal_load((const v4u*)(ZS + row * 512 + col));
;                     const f32x4 a0 = acc[ai][bj][m][0], a1 = acc[ai][bj][m][1];
;                     v4u w;
;                     w.x = pg8::cvt_pk_bf16(bflo(y.x) * sigm(a0[0] + b0[0]) * bflo(z.x), bfhi(y.x) * sigm(a0[1] + b0[1]) * bfhi(z.x));
;                     w.y = pg8::cvt_pk_bf16(bflo(y.y) * sigm(a0[2] + b0[2]) * bflo(z.y), bfhi(y.y) * sigm(a0[3] + b0[3]) * bfhi(z.y));
;                     w.z = pg8::cvt_pk_bf16(bflo(y.z) * sigm(a1[0] + b1[0]) * bflo(z.z), bfhi(y.z) * sigm(a1[1] + b1[1]) * bfhi(z.z));
;                     w.w = pg8::cvt_pk_bf16(bflo(y.w) * sigm(a1[2] + b1[2]) * bflo(z.w), bfhi(y.w) * sigm(a1[3] + b1[3]) * bfhi(z.w));
;                     *(v4u*)(A5 + row * 1024 + 512 + col) = w;
;                 }
;         }
;     }
	v_lshlrev_b32_e32 v146, 16, v242
	v_and_b32_e32 v147, 0xffff0000, v242
	v_lshlrev_b32_e32 v148, 16, v243
	v_and_b32_e32 v149, 0xffff0000, v243
	v_lshlrev_b32_e32 v150, 16, v244
	v_and_b32_e32 v151, 0xffff0000, v244
	v_lshlrev_b32_e32 v166, 16, v245
	v_and_b32_e32 v167, 0xffff0000, v245
	v_mul_f32_e32 v70, v70, v146
	v_mul_f32_e32 v71, v71, v147
	v_mul_f32_e32 v72, v72, v148
	v_mul_f32_e32 v73, v73, v149
	v_mul_f32_e32 v66, v66, v150
	v_mul_f32_e32 v67, v67, v151
	v_mul_f32_e32 v68, v68, v166
	v_mul_f32_e32 v69, v69, v167
	v_lshlrev_b32_e32 v146, 16, v246
	v_and_b32_e32 v147, 0xffff0000, v246
	v_lshlrev_b32_e32 v148, 16, v247
	v_and_b32_e32 v149, 0xffff0000, v247
	v_lshlrev_b32_e32 v150, 16, v248
	v_and_b32_e32 v151, 0xffff0000, v248
	v_lshlrev_b32_e32 v166, 16, v249
	v_and_b32_e32 v167, 0xffff0000, v249
	v_mul_f32_e32 v70, v70, v146
	v_mul_f32_e32 v71, v71, v147
	v_mul_f32_e32 v72, v72, v148
	v_mul_f32_e32 v73, v73, v149
	v_mul_f32_e32 v66, v66, v150
	v_mul_f32_e32 v67, v67, v151
	v_mul_f32_e32 v68, v68, v166
	v_mul_f32_e32 v69, v69, v167
	v_cvt_pk_bf16_f32 v142, v70, v71
	v_cvt_pk_bf16_f32 v143, v72, v73
	v_cvt_pk_bf16_f32 v144, v66, v67
	v_cvt_pk_bf16_f32 v145, v68, v69
	global_store_dwordx4 v[160:161], v[142:145], off offset:1024
	global_load_dwordx4 v[242:245], v[162:163], off offset:256 nt
	global_load_dwordx4 v[246:249], v[184:185], off offset:256 nt
	v_add_f32_e32 v62, v62, v170
	v_add_f32_e32 v63, v63, v171
	v_add_f32_e32 v64, v64, v172
	v_add_f32_e32 v65, v65, v173
	v_add_f32_e32 v58, v58, v174
	v_add_f32_e32 v59, v59, v175
	v_add_f32_e32 v60, v60, v176
	v_add_f32_e32 v61, v61, v177
	v_mul_f32_e32 v62, 0xbfb8aa3b, v62
	v_mul_f32_e32 v63, 0xbfb8aa3b, v63
	v_mul_f32_e32 v64, 0xbfb8aa3b, v64
	v_mul_f32_e32 v65, 0xbfb8aa3b, v65
	v_mul_f32_e32 v58, 0xbfb8aa3b, v58
	v_mul_f32_e32 v59, 0xbfb8aa3b, v59
	v_mul_f32_e32 v60, 0xbfb8aa3b, v60
	v_mul_f32_e32 v61, 0xbfb8aa3b, v61
	v_exp_f32_e32 v62, v62
	v_exp_f32_e32 v63, v63
	v_exp_f32_e32 v64, v64
	v_exp_f32_e32 v65, v65
	v_exp_f32_e32 v58, v58
	v_exp_f32_e32 v59, v59
	v_exp_f32_e32 v60, v60
	v_exp_f32_e32 v61, v61
	v_add_f32_e32 v62, 1.0, v62
	v_add_f32_e32 v63, 1.0, v63
	v_add_f32_e32 v64, 1.0, v64
	v_add_f32_e32 v65, 1.0, v65
	v_add_f32_e32 v58, 1.0, v58
	v_add_f32_e32 v59, 1.0, v59
	v_add_f32_e32 v60, 1.0, v60
	v_add_f32_e32 v61, 1.0, v61
	v_rcp_f32_e32 v62, v62
	v_rcp_f32_e32 v63, v63
	v_rcp_f32_e32 v64, v64
	v_rcp_f32_e32 v65, v65
	v_rcp_f32_e32 v58, v58
	v_rcp_f32_e32 v59, v59
	v_rcp_f32_e32 v60, v60
	v_rcp_f32_e32 v61, v61
	s_waitcnt vmcnt(21)
	v_lshlrev_b32_e32 v146, 16, v186
	v_and_b32_e32 v147, 0xffff0000, v186
	v_lshlrev_b32_e32 v148, 16, v187
	v_and_b32_e32 v149, 0xffff0000, v187
	v_lshlrev_b32_e32 v150, 16, v188
	v_and_b32_e32 v151, 0xffff0000, v188
	v_lshlrev_b32_e32 v166, 16, v189
	v_and_b32_e32 v167, 0xffff0000, v189
	v_mul_f32_e32 v62, v62, v146
	v_mul_f32_e32 v63, v63, v147
	v_mul_f32_e32 v64, v64, v148
	v_mul_f32_e32 v65, v65, v149
	v_mul_f32_e32 v58, v58, v150
	v_mul_f32_e32 v59, v59, v151
	v_mul_f32_e32 v60, v60, v166
	v_mul_f32_e32 v61, v61, v167
	v_lshlrev_b32_e32 v146, 16, v190
	v_and_b32_e32 v147, 0xffff0000, v190
	v_lshlrev_b32_e32 v148, 16, v191
	v_and_b32_e32 v149, 0xffff0000, v191
	v_lshlrev_b32_e32 v150, 16, v192
	v_and_b32_e32 v151, 0xffff0000, v192
	v_lshlrev_b32_e32 v166, 16, v193
	v_and_b32_e32 v167, 0xffff0000, v193
	v_mul_f32_e32 v62, v62, v146
	v_mul_f32_e32 v63, v63, v147
	v_mul_f32_e32 v64, v64, v148
	v_mul_f32_e32 v65, v65, v149
	v_mul_f32_e32 v58, v58, v150
	v_mul_f32_e32 v59, v59, v151
	v_mul_f32_e32 v60, v60, v166
	v_mul_f32_e32 v61, v61, v167
	v_cvt_pk_bf16_f32 v138, v62, v63
	v_cvt_pk_bf16_f32 v139, v64, v65
	v_cvt_pk_bf16_f32 v140, v58, v59
	v_cvt_pk_bf16_f32 v141, v60, v61
	global_store_dwordx4 v[182:183], v[138:141], off offset:1280
	v_lshl_add_u64 v[182:183], v[182:183], 0, v[178:179]
	v_add_f32_e32 v54, v54, v170
	v_add_f32_e32 v55, v55, v171
	v_add_f32_e32 v56, v56, v172
	v_add_f32_e32 v57, v57, v173
	v_add_f32_e32 v50, v50, v174
	v_add_f32_e32 v51, v51, v175
	v_add_f32_e32 v52, v52, v176
	v_add_f32_e32 v53, v53, v177
	v_mul_f32_e32 v54, 0xbfb8aa3b, v54
	v_mul_f32_e32 v55, 0xbfb8aa3b, v55
	v_mul_f32_e32 v56, 0xbfb8aa3b, v56
	v_mul_f32_e32 v57, 0xbfb8aa3b, v57
	v_mul_f32_e32 v50, 0xbfb8aa3b, v50
	v_mul_f32_e32 v51, 0xbfb8aa3b, v51
	v_mul_f32_e32 v52, 0xbfb8aa3b, v52
	v_mul_f32_e32 v53, 0xbfb8aa3b, v53
	v_exp_f32_e32 v54, v54
	v_exp_f32_e32 v55, v55
	v_exp_f32_e32 v56, v56
	v_exp_f32_e32 v57, v57
	v_exp_f32_e32 v50, v50
	v_exp_f32_e32 v51, v51
	v_exp_f32_e32 v52, v52
	v_exp_f32_e32 v53, v53
	v_add_f32_e32 v54, 1.0, v54
	v_add_f32_e32 v55, 1.0, v55
	v_add_f32_e32 v56, 1.0, v56
	v_add_f32_e32 v57, 1.0, v57
	v_add_f32_e32 v50, 1.0, v50
	v_add_f32_e32 v51, 1.0, v51
	v_add_f32_e32 v52, 1.0, v52
	v_add_f32_e32 v53, 1.0, v53
	v_rcp_f32_e32 v54, v54
	v_rcp_f32_e32 v55, v55
	v_rcp_f32_e32 v56, v56
	v_rcp_f32_e32 v57, v57
	v_rcp_f32_e32 v50, v50
	v_rcp_f32_e32 v51, v51
	v_rcp_f32_e32 v52, v52
	v_rcp_f32_e32 v53, v53
	s_waitcnt vmcnt(19)
; __device__ __forceinline__ unsigned cvt_pk_bf16(float lo, float hi) { unsigned r; asm volatile("v_cvt_pk_bf16_f32 %0, %1, %2" : "=v"(r) : "v"(lo), "v"(hi)); return r; }
; __device__ __forceinline__ float bflo(unsigned w) { return __uint_as_float(w << 16); }
; __device__ __forceinline__ float bfhi(unsigned w) { return __uint_as_float(w & 0xffff0000u); }
; __device__ __forceinline__ float sigm(float v) { return frcp(1.f + fexp2(-LOG2E * v)); }
;     __device__ __forceinline__ void operator()(const f32x4 (&acc)[2][2][4][2], const Unit& u, int wr, int wc, int fr, int fq) const { if (u.pn >= 9) g(acc, u, wr, wc, fr, fq); else a(acc, u, wr, wc, fr, fq); }
;     __device__ __forceinline__ void operator()(const f32x4 (&acc)[2][2][4][2], const Unit& u, int wr, int wc, int fr, int fq) const {
;         const int row0 = u.pm * 256 + wr * 64 + fr, c8 = wc * 32 + 8 * fq;
; #pragma unroll
;         for (int bj = 0; bj < 2; ++bj) {
;             const int col = u.pn * 256 + bj * 128 + c8;
;             const f32x4 b0 = *(const f32x4*)(b_glu + col), b1 = *(const f32x4*)(b_glu + col + 4);
; #pragma unroll
;             for (int ai = 0; ai < 2; ++ai)
; #pragma unroll
;                 for (int m = 0; m < 4; ++m) {
;                     const size_t row = (size_t)(row0 + ai * 128 + m * 16);
;                     const v4u y = __builtin_nontemporal_load((const v4u*)(YG + row * 512 + col)), z = __builtin_nontemporal_load((const v4u*)(ZS + row * 512 + col));
;                     const f32x4 a0 = acc[ai][bj][m][0], a1 = acc[ai][bj][m][1];
;                     v4u w;
;                     w.x = pg8::cvt_pk_bf16(bflo(y.x) * sigm(a0[0] + b0[0]) * bflo(z.x), bfhi(y.x) * sigm(a0[1] + b0[1]) * bfhi(z.x));
;                     w.y = pg8::cvt_pk_bf16(bflo(y.y) * sigm(a0[2] + b0[2]) * bflo(z.y), bfhi(y.y) * sigm(a0[3] + b0[3]) * bfhi(z.y));
;                     w.z = pg8::cvt_pk_bf16(bflo(y.z) * sigm(a1[0] + b1[0]) * bflo(z.z), bfhi(y.z) * sigm(a1[1] + b1[1]) * bfhi(z.z));
;                     w.w = pg8::cvt_pk_bf16(bflo(y.w) * sigm(a1[2] + b1[2]) * bflo(z.w), bfhi(y.w) * sigm(a1[3] + b1[3]) * bfhi(z.w));
;                     *(v4u*)(A5 + row * 1024 + 512 + col) = w;
;                 }
;         }
;     }
	v_lshlrev_b32_e32 v146, 16, v194
	v_and_b32_e32 v147, 0xffff0000, v194
	v_lshlrev_b32_e32 v148, 16, v195
	v_and_b32_e32 v149, 0xffff0000, v195
	v_lshlrev_b32_e32 v150, 16, v196
	v_and_b32_e32 v151, 0xffff0000, v196
	v_lshlrev_b32_e32 v166, 16, v197
	v_and_b32_e32 v167, 0xffff0000, v197
	v_mul_f32_e32 v54, v54, v146
	v_mul_f32_e32 v55, v55, v147
	v_mul_f32_e32 v56, v56, v148
	v_mul_f32_e32 v57, v57, v149
	v_mul_f32_e32 v50, v50, v150
	v_mul_f32_e32 v51, v51, v151
	v_mul_f32_e32 v52, v52, v166
	v_mul_f32_e32 v53, v53, v167
	v_lshlrev_b32_e32 v146, 16, v198
	v_and_b32_e32 v147, 0xffff0000, v198
	v_lshlrev_b32_e32 v148, 16, v199
	v_and_b32_e32 v149, 0xffff0000, v199
	v_lshlrev_b32_e32 v150, 16, v200
	v_and_b32_e32 v151, 0xffff0000, v200
	v_lshlrev_b32_e32 v166, 16, v201
	v_and_b32_e32 v167, 0xffff0000, v201
	v_mul_f32_e32 v54, v54, v146
	v_mul_f32_e32 v55, v55, v147
	v_mul_f32_e32 v56, v56, v148
	v_mul_f32_e32 v57, v57, v149
	v_mul_f32_e32 v50, v50, v150
	v_mul_f32_e32 v51, v51, v151
	v_mul_f32_e32 v52, v52, v166
	v_mul_f32_e32 v53, v53, v167
	v_cvt_pk_bf16_f32 v142, v54, v55
	v_cvt_pk_bf16_f32 v143, v56, v57
	v_cvt_pk_bf16_f32 v144, v50, v51
	v_cvt_pk_bf16_f32 v145, v52, v53
	global_store_dwordx4 v[182:183], v[142:145], off offset:1280
	v_lshl_add_u64 v[182:183], v[182:183], 0, v[178:179]
	v_add_f32_e32 v46, v46, v170
	v_add_f32_e32 v47, v47, v171
	v_add_f32_e32 v48, v48, v172
	v_add_f32_e32 v49, v49, v173
	v_add_f32_e32 v42, v42, v174
	v_add_f32_e32 v43, v43, v175
	v_add_f32_e32 v44, v44, v176
	v_add_f32_e32 v45, v45, v177
	v_mul_f32_e32 v46, 0xbfb8aa3b, v46
	v_mul_f32_e32 v47, 0xbfb8aa3b, v47
	v_mul_f32_e32 v48, 0xbfb8aa3b, v48
	v_mul_f32_e32 v49, 0xbfb8aa3b, v49
	v_mul_f32_e32 v42, 0xbfb8aa3b, v42
	v_mul_f32_e32 v43, 0xbfb8aa3b, v43
	v_mul_f32_e32 v44, 0xbfb8aa3b, v44
	v_mul_f32_e32 v45, 0xbfb8aa3b, v45
	v_exp_f32_e32 v46, v46
	v_exp_f32_e32 v47, v47
	v_exp_f32_e32 v48, v48
	v_exp_f32_e32 v49, v49
	v_exp_f32_e32 v42, v42
	v_exp_f32_e32 v43, v43
	v_exp_f32_e32 v44, v44
	v_exp_f32_e32 v45, v45
	v_add_f32_e32 v46, 1.0, v46
	v_add_f32_e32 v47, 1.0, v47
	v_add_f32_e32 v48, 1.0, v48
	v_add_f32_e32 v49, 1.0, v49
	v_add_f32_e32 v42, 1.0, v42
	v_add_f32_e32 v43, 1.0, v43
	v_add_f32_e32 v44, 1.0, v44
	v_add_f32_e32 v45, 1.0, v45
	v_rcp_f32_e32 v46, v46
	v_rcp_f32_e32 v47, v47
	v_rcp_f32_e32 v48, v48
	v_rcp_f32_e32 v49, v49
	v_rcp_f32_e32 v42, v42
	v_rcp_f32_e32 v43, v43
	v_rcp_f32_e32 v44, v44
	v_rcp_f32_e32 v45, v45
	s_waitcnt vmcnt(17)
	v_lshlrev_b32_e32 v146, 16, v202
	v_and_b32_e32 v147, 0xffff0000, v202
	v_lshlrev_b32_e32 v148, 16, v203
	v_and_b32_e32 v149, 0xffff0000, v203
	v_lshlrev_b32_e32 v150, 16, v204
	v_and_b32_e32 v151, 0xffff0000, v204
	v_lshlrev_b32_e32 v166, 16, v205
	v_and_b32_e32 v167, 0xffff0000, v205
	v_mul_f32_e32 v46, v46, v146
	v_mul_f32_e32 v47, v47, v147
	v_mul_f32_e32 v48, v48, v148
	v_mul_f32_e32 v49, v49, v149
	v_mul_f32_e32 v42, v42, v150
	v_mul_f32_e32 v43, v43, v151
	v_mul_f32_e32 v44, v44, v166
	v_mul_f32_e32 v45, v45, v167
	v_lshlrev_b32_e32 v146, 16, v206
	v_and_b32_e32 v147, 0xffff0000, v206
	v_lshlrev_b32_e32 v148, 16, v207
	v_and_b32_e32 v149, 0xffff0000, v207
	v_lshlrev_b32_e32 v150, 16, v208
	v_and_b32_e32 v151, 0xffff0000, v208
	v_lshlrev_b32_e32 v166, 16, v209
	v_and_b32_e32 v167, 0xffff0000, v209
	v_mul_f32_e32 v46, v46, v146
	v_mul_f32_e32 v47, v47, v147
	v_mul_f32_e32 v48, v48, v148
	v_mul_f32_e32 v49, v49, v149
	v_mul_f32_e32 v42, v42, v150
	v_mul_f32_e32 v43, v43, v151
	v_mul_f32_e32 v44, v44, v166
	v_mul_f32_e32 v45, v45, v167
	v_cvt_pk_bf16_f32 v138, v46, v47
	v_cvt_pk_bf16_f32 v139, v48, v49
	v_cvt_pk_bf16_f32 v140, v42, v43
	v_cvt_pk_bf16_f32 v141, v44, v45
	global_store_dwordx4 v[182:183], v[138:141], off offset:1280
	v_lshl_add_u64 v[182:183], v[182:183], 0, v[178:179]
	v_add_f32_e32 v38, v38, v170
	v_add_f32_e32 v39, v39, v171
	v_add_f32_e32 v40, v40, v172
	v_add_f32_e32 v41, v41, v173
	v_add_f32_e32 v34, v34, v174
	v_add_f32_e32 v35, v35, v175
	v_add_f32_e32 v36, v36, v176
	v_add_f32_e32 v37, v37, v177
	v_mul_f32_e32 v38, 0xbfb8aa3b, v38
	v_mul_f32_e32 v39, 0xbfb8aa3b, v39
	v_mul_f32_e32 v40, 0xbfb8aa3b, v40
	v_mul_f32_e32 v41, 0xbfb8aa3b, v41
	v_mul_f32_e32 v34, 0xbfb8aa3b, v34
	v_mul_f32_e32 v35, 0xbfb8aa3b, v35
	v_mul_f32_e32 v36, 0xbfb8aa3b, v36
	v_mul_f32_e32 v37, 0xbfb8aa3b, v37
	v_exp_f32_e32 v38, v38
	v_exp_f32_e32 v39, v39
	v_exp_f32_e32 v40, v40
	v_exp_f32_e32 v41, v41
	v_exp_f32_e32 v34, v34
	v_exp_f32_e32 v35, v35
	v_exp_f32_e32 v36, v36
	v_exp_f32_e32 v37, v37
	v_add_f32_e32 v38, 1.0, v38
	v_add_f32_e32 v39, 1.0, v39
	v_add_f32_e32 v40, 1.0, v40
	v_add_f32_e32 v41, 1.0, v41
	v_add_f32_e32 v34, 1.0, v34
	v_add_f32_e32 v35, 1.0, v35
	v_add_f32_e32 v36, 1.0, v36
	v_add_f32_e32 v37, 1.0, v37
	v_rcp_f32_e32 v38, v38
	v_rcp_f32_e32 v39, v39
	v_rcp_f32_e32 v40, v40
	v_rcp_f32_e32 v41, v41
	v_rcp_f32_e32 v34, v34
	v_rcp_f32_e32 v35, v35
	v_rcp_f32_e32 v36, v36
	v_rcp_f32_e32 v37, v37
	s_waitcnt vmcnt(15)
; __device__ __forceinline__ unsigned cvt_pk_bf16(float lo, float hi) { unsigned r; asm volatile("v_cvt_pk_bf16_f32 %0, %1, %2" : "=v"(r) : "v"(lo), "v"(hi)); return r; }
; __device__ __forceinline__ float bflo(unsigned w) { return __uint_as_float(w << 16); }
; __device__ __forceinline__ float bfhi(unsigned w) { return __uint_as_float(w & 0xffff0000u); }
; __device__ __forceinline__ float sigm(float v) { return frcp(1.f + fexp2(-LOG2E * v)); }
;     __device__ __forceinline__ void operator()(const f32x4 (&acc)[2][2][4][2], const Unit& u, int wr, int wc, int fr, int fq) const { if (u.pn >= 9) g(acc, u, wr, wc, fr, fq); else a(acc, u, wr, wc, fr, fq); }
;     __device__ __forceinline__ void operator()(const f32x4 (&acc)[2][2][4][2], const Unit& u, int wr, int wc, int fr, int fq) const {
;         const int row0 = u.pm * 256 + wr * 64 + fr, c8 = wc * 32 + 8 * fq;
; #pragma unroll
;         for (int bj = 0; bj < 2; ++bj) {
;             const int col = u.pn * 256 + bj * 128 + c8;
;             const f32x4 b0 = *(const f32x4*)(b_glu + col), b1 = *(const f32x4*)(b_glu + col + 4);
; #pragma unroll
;             for (int ai = 0; ai < 2; ++ai)
; #pragma unroll
;                 for (int m = 0; m < 4; ++m) {
;                     const size_t row = (size_t)(row0 + ai * 128 + m * 16);
;                     const v4u y = __builtin_nontemporal_load((const v4u*)(YG + row * 512 + col)), z = __builtin_nontemporal_load((const v4u*)(ZS + row * 512 + col));
;                     const f32x4 a0 = acc[ai][bj][m][0], a1 = acc[ai][bj][m][1];
;                     v4u w;
;                     w.x = pg8::cvt_pk_bf16(bflo(y.x) * sigm(a0[0] + b0[0]) * bflo(z.x), bfhi(y.x) * sigm(a0[1] + b0[1]) * bfhi(z.x));
;                     w.y = pg8::cvt_pk_bf16(bflo(y.y) * sigm(a0[2] + b0[2]) * bflo(z.y), bfhi(y.y) * sigm(a0[3] + b0[3]) * bfhi(z.y));
;                     w.z = pg8::cvt_pk_bf16(bflo(y.z) * sigm(a1[0] + b1[0]) * bflo(z.z), bfhi(y.z) * sigm(a1[1] + b1[1]) * bfhi(z.z));
;                     w.w = pg8::cvt_pk_bf16(bflo(y.w) * sigm(a1[2] + b1[2]) * bflo(z.w), bfhi(y.w) * sigm(a1[3] + b1[3]) * bfhi(z.w));
;                     *(v4u*)(A5 + row * 1024 + 512 + col) = w;
;                 }
;         }
;     }
	v_lshlrev_b32_e32 v146, 16, v210
	v_and_b32_e32 v147, 0xffff0000, v210
	v_lshlrev_b32_e32 v148, 16, v211
	v_and_b32_e32 v149, 0xffff0000, v211
	v_lshlrev_b32_e32 v150, 16, v212
	v_and_b32_e32 v151, 0xffff0000, v212
	v_lshlrev_b32_e32 v166, 16, v213
	v_and_b32_e32 v167, 0xffff0000, v213
	v_mul_f32_e32 v38, v38, v146
	v_mul_f32_e32 v39, v39, v147
	v_mul_f32_e32 v40, v40, v148
	v_mul_f32_e32 v41, v41, v149
	v_mul_f32_e32 v34, v34, v150
	v_mul_f32_e32 v35, v35, v151
	v_mul_f32_e32 v36, v36, v166
	v_mul_f32_e32 v37, v37, v167
	v_lshlrev_b32_e32 v146, 16, v214
	v_and_b32_e32 v147, 0xffff0000, v214
	v_lshlrev_b32_e32 v148, 16, v215
	v_and_b32_e32 v149, 0xffff0000, v215
	v_lshlrev_b32_e32 v150, 16, v216
	v_and_b32_e32 v151, 0xffff0000, v216
	v_lshlrev_b32_e32 v166, 16, v217
	v_and_b32_e32 v167, 0xffff0000, v217
	v_mul_f32_e32 v38, v38, v146
	v_mul_f32_e32 v39, v39, v147
	v_mul_f32_e32 v40, v40, v148
	v_mul_f32_e32 v41, v41, v149
	v_mul_f32_e32 v34, v34, v150
	v_mul_f32_e32 v35, v35, v151
	v_mul_f32_e32 v36, v36, v166
	v_mul_f32_e32 v37, v37, v167
	v_cvt_pk_bf16_f32 v142, v38, v39
	v_cvt_pk_bf16_f32 v143, v40, v41
	v_cvt_pk_bf16_f32 v144, v34, v35
	v_cvt_pk_bf16_f32 v145, v36, v37
	global_store_dwordx4 v[182:183], v[142:145], off offset:1280
	v_lshl_add_u64 v[182:183], v[182:183], 0, v[180:181]
	v_add_f32_e32 v30, v30, v170
	v_add_f32_e32 v31, v31, v171
	v_add_f32_e32 v32, v32, v172
	v_add_f32_e32 v33, v33, v173
	v_add_f32_e32 v26, v26, v174
	v_add_f32_e32 v27, v27, v175
	v_add_f32_e32 v28, v28, v176
	v_add_f32_e32 v29, v29, v177
	v_mul_f32_e32 v30, 0xbfb8aa3b, v30
	v_mul_f32_e32 v31, 0xbfb8aa3b, v31
	v_mul_f32_e32 v32, 0xbfb8aa3b, v32
	v_mul_f32_e32 v33, 0xbfb8aa3b, v33
	v_mul_f32_e32 v26, 0xbfb8aa3b, v26
	v_mul_f32_e32 v27, 0xbfb8aa3b, v27
	v_mul_f32_e32 v28, 0xbfb8aa3b, v28
	v_mul_f32_e32 v29, 0xbfb8aa3b, v29
	v_exp_f32_e32 v30, v30
	v_exp_f32_e32 v31, v31
	v_exp_f32_e32 v32, v32
	v_exp_f32_e32 v33, v33
	v_exp_f32_e32 v26, v26
	v_exp_f32_e32 v27, v27
	v_exp_f32_e32 v28, v28
	v_exp_f32_e32 v29, v29
	v_add_f32_e32 v30, 1.0, v30
	v_add_f32_e32 v31, 1.0, v31
	v_add_f32_e32 v32, 1.0, v32
	v_add_f32_e32 v33, 1.0, v33
	v_add_f32_e32 v26, 1.0, v26
	v_add_f32_e32 v27, 1.0, v27
	v_add_f32_e32 v28, 1.0, v28
	v_add_f32_e32 v29, 1.0, v29
	v_rcp_f32_e32 v30, v30
	v_rcp_f32_e32 v31, v31
	v_rcp_f32_e32 v32, v32
	v_rcp_f32_e32 v33, v33
	v_rcp_f32_e32 v26, v26
	v_rcp_f32_e32 v27, v27
	v_rcp_f32_e32 v28, v28
	v_rcp_f32_e32 v29, v29
	s_waitcnt vmcnt(13)
	v_lshlrev_b32_e32 v146, 16, v218
	v_and_b32_e32 v147, 0xffff0000, v218
	v_lshlrev_b32_e32 v148, 16, v219
	v_and_b32_e32 v149, 0xffff0000, v219
	v_lshlrev_b32_e32 v150, 16, v220
	v_and_b32_e32 v151, 0xffff0000, v220
	v_lshlrev_b32_e32 v166, 16, v221
	v_and_b32_e32 v167, 0xffff0000, v221
	v_mul_f32_e32 v30, v30, v146
	v_mul_f32_e32 v31, v31, v147
	v_mul_f32_e32 v32, v32, v148
	v_mul_f32_e32 v33, v33, v149
	v_mul_f32_e32 v26, v26, v150
	v_mul_f32_e32 v27, v27, v151
	v_mul_f32_e32 v28, v28, v166
	v_mul_f32_e32 v29, v29, v167
	v_lshlrev_b32_e32 v146, 16, v222
	v_and_b32_e32 v147, 0xffff0000, v222
	v_lshlrev_b32_e32 v148, 16, v223
	v_and_b32_e32 v149, 0xffff0000, v223
	v_lshlrev_b32_e32 v150, 16, v224
	v_and_b32_e32 v151, 0xffff0000, v224
	v_lshlrev_b32_e32 v166, 16, v225
	v_and_b32_e32 v167, 0xffff0000, v225
	v_mul_f32_e32 v30, v30, v146
	v_mul_f32_e32 v31, v31, v147
	v_mul_f32_e32 v32, v32, v148
	v_mul_f32_e32 v33, v33, v149
	v_mul_f32_e32 v26, v26, v150
	v_mul_f32_e32 v27, v27, v151
	v_mul_f32_e32 v28, v28, v166
	v_mul_f32_e32 v29, v29, v167
	v_cvt_pk_bf16_f32 v138, v30, v31
	v_cvt_pk_bf16_f32 v139, v32, v33
	v_cvt_pk_bf16_f32 v140, v26, v27
	v_cvt_pk_bf16_f32 v141, v28, v29
	global_store_dwordx4 v[182:183], v[138:141], off offset:1280
	v_lshl_add_u64 v[182:183], v[182:183], 0, v[178:179]
	v_add_f32_e32 v22, v22, v170
	v_add_f32_e32 v23, v23, v171
	v_add_f32_e32 v24, v24, v172
	v_add_f32_e32 v25, v25, v173
	v_add_f32_e32 v18, v18, v174
	v_add_f32_e32 v19, v19, v175
	v_add_f32_e32 v20, v20, v176
	v_add_f32_e32 v21, v21, v177
	v_mul_f32_e32 v22, 0xbfb8aa3b, v22
	v_mul_f32_e32 v23, 0xbfb8aa3b, v23
	v_mul_f32_e32 v24, 0xbfb8aa3b, v24
	v_mul_f32_e32 v25, 0xbfb8aa3b, v25
	v_mul_f32_e32 v18, 0xbfb8aa3b, v18
	v_mul_f32_e32 v19, 0xbfb8aa3b, v19
	v_mul_f32_e32 v20, 0xbfb8aa3b, v20
	v_mul_f32_e32 v21, 0xbfb8aa3b, v21
	v_exp_f32_e32 v22, v22
	v_exp_f32_e32 v23, v23
	v_exp_f32_e32 v24, v24
	v_exp_f32_e32 v25, v25
	v_exp_f32_e32 v18, v18
	v_exp_f32_e32 v19, v19
	v_exp_f32_e32 v20, v20
	v_exp_f32_e32 v21, v21
	v_add_f32_e32 v22, 1.0, v22
	v_add_f32_e32 v23, 1.0, v23
	v_add_f32_e32 v24, 1.0, v24
	v_add_f32_e32 v25, 1.0, v25
	v_add_f32_e32 v18, 1.0, v18
	v_add_f32_e32 v19, 1.0, v19
	v_add_f32_e32 v20, 1.0, v20
	v_add_f32_e32 v21, 1.0, v21
	v_rcp_f32_e32 v22, v22
	v_rcp_f32_e32 v23, v23
	v_rcp_f32_e32 v24, v24
	v_rcp_f32_e32 v25, v25
	v_rcp_f32_e32 v18, v18
	v_rcp_f32_e32 v19, v19
	v_rcp_f32_e32 v20, v20
	v_rcp_f32_e32 v21, v21
	s_waitcnt vmcnt(11)
; __device__ __forceinline__ unsigned cvt_pk_bf16(float lo, float hi) { unsigned r; asm volatile("v_cvt_pk_bf16_f32 %0, %1, %2" : "=v"(r) : "v"(lo), "v"(hi)); return r; }
; __device__ __forceinline__ float bflo(unsigned w) { return __uint_as_float(w << 16); }
; __device__ __forceinline__ float bfhi(unsigned w) { return __uint_as_float(w & 0xffff0000u); }
; __device__ __forceinline__ float sigm(float v) { return frcp(1.f + fexp2(-LOG2E * v)); }
;     __device__ __forceinline__ void operator()(const f32x4 (&acc)[2][2][4][2], const Unit& u, int wr, int wc, int fr, int fq) const { if (u.pn >= 9) g(acc, u, wr, wc, fr, fq); else a(acc, u, wr, wc, fr, fq); }
;     __device__ __forceinline__ void operator()(const f32x4 (&acc)[2][2][4][2], const Unit& u, int wr, int wc, int fr, int fq) const {
;         const int row0 = u.pm * 256 + wr * 64 + fr, c8 = wc * 32 + 8 * fq;
; #pragma unroll
;         for (int bj = 0; bj < 2; ++bj) {
;             const int col = u.pn * 256 + bj * 128 + c8;
;             const f32x4 b0 = *(const f32x4*)(b_glu + col), b1 = *(const f32x4*)(b_glu + col + 4);
; #pragma unroll
;             for (int ai = 0; ai < 2; ++ai)
; #pragma unroll
;                 for (int m = 0; m < 4; ++m) {
;                     const size_t row = (size_t)(row0 + ai * 128 + m * 16);
;                     const v4u y = __builtin_nontemporal_load((const v4u*)(YG + row * 512 + col)), z = __builtin_nontemporal_load((const v4u*)(ZS + row * 512 + col));
;                     const f32x4 a0 = acc[ai][bj][m][0], a1 = acc[ai][bj][m][1];
;                     v4u w;
;                     w.x = pg8::cvt_pk_bf16(bflo(y.x) * sigm(a0[0] + b0[0]) * bflo(z.x), bfhi(y.x) * sigm(a0[1] + b0[1]) * bfhi(z.x));
;                     w.y = pg8::cvt_pk_bf16(bflo(y.y) * sigm(a0[2] + b0[2]) * bflo(z.y), bfhi(y.y) * sigm(a0[3] + b0[3]) * bfhi(z.y));
;                     w.z = pg8::cvt_pk_bf16(bflo(y.z) * sigm(a1[0] + b1[0]) * bflo(z.z), bfhi(y.z) * sigm(a1[1] + b1[1]) * bfhi(z.z));
;                     w.w = pg8::cvt_pk_bf16(bflo(y.w) * sigm(a1[2] + b1[2]) * bflo(z.w), bfhi(y.w) * sigm(a1[3] + b1[3]) * bfhi(z.w));
;                     *(v4u*)(A5 + row * 1024 + 512 + col) = w;
;                 }
;         }
;     }
	v_lshlrev_b32_e32 v146, 16, v226
	v_and_b32_e32 v147, 0xffff0000, v226
	v_lshlrev_b32_e32 v148, 16, v227
	v_and_b32_e32 v149, 0xffff0000, v227
	v_lshlrev_b32_e32 v150, 16, v228
	v_and_b32_e32 v151, 0xffff0000, v228
	v_lshlrev_b32_e32 v166, 16, v229
	v_and_b32_e32 v167, 0xffff0000, v229
	v_mul_f32_e32 v22, v22, v146
	v_mul_f32_e32 v23, v23, v147
	v_mul_f32_e32 v24, v24, v148
	v_mul_f32_e32 v25, v25, v149
	v_mul_f32_e32 v18, v18, v150
	v_mul_f32_e32 v19, v19, v151
	v_mul_f32_e32 v20, v20, v166
	v_mul_f32_e32 v21, v21, v167
	v_lshlrev_b32_e32 v146, 16, v230
	v_and_b32_e32 v147, 0xffff0000, v230
	v_lshlrev_b32_e32 v148, 16, v231
	v_and_b32_e32 v149, 0xffff0000, v231
	v_lshlrev_b32_e32 v150, 16, v232
	v_and_b32_e32 v151, 0xffff0000, v232
	v_lshlrev_b32_e32 v166, 16, v233
	v_and_b32_e32 v167, 0xffff0000, v233
	v_mul_f32_e32 v22, v22, v146
	v_mul_f32_e32 v23, v23, v147
	v_mul_f32_e32 v24, v24, v148
	v_mul_f32_e32 v25, v25, v149
	v_mul_f32_e32 v18, v18, v150
	v_mul_f32_e32 v19, v19, v151
	v_mul_f32_e32 v20, v20, v166
	v_mul_f32_e32 v21, v21, v167
	v_cvt_pk_bf16_f32 v142, v22, v23
	v_cvt_pk_bf16_f32 v143, v24, v25
	v_cvt_pk_bf16_f32 v144, v18, v19
	v_cvt_pk_bf16_f32 v145, v20, v21
	global_store_dwordx4 v[182:183], v[142:145], off offset:1280
	v_lshl_add_u64 v[182:183], v[182:183], 0, v[178:179]
	v_add_f32_e32 v14, v14, v170
	v_add_f32_e32 v15, v15, v171
	v_add_f32_e32 v16, v16, v172
	v_add_f32_e32 v17, v17, v173
	v_add_f32_e32 v10, v10, v174
	v_add_f32_e32 v11, v11, v175
	v_add_f32_e32 v12, v12, v176
	v_add_f32_e32 v13, v13, v177
	v_mul_f32_e32 v14, 0xbfb8aa3b, v14
	v_mul_f32_e32 v15, 0xbfb8aa3b, v15
	v_mul_f32_e32 v16, 0xbfb8aa3b, v16
	v_mul_f32_e32 v17, 0xbfb8aa3b, v17
	v_mul_f32_e32 v10, 0xbfb8aa3b, v10
	v_mul_f32_e32 v11, 0xbfb8aa3b, v11
	v_mul_f32_e32 v12, 0xbfb8aa3b, v12
	v_mul_f32_e32 v13, 0xbfb8aa3b, v13
	v_exp_f32_e32 v14, v14
	v_exp_f32_e32 v15, v15
	v_exp_f32_e32 v16, v16
	v_exp_f32_e32 v17, v17
	v_exp_f32_e32 v10, v10
	v_exp_f32_e32 v11, v11
	v_exp_f32_e32 v12, v12
	v_exp_f32_e32 v13, v13
	v_add_f32_e32 v14, 1.0, v14
	v_add_f32_e32 v15, 1.0, v15
	v_add_f32_e32 v16, 1.0, v16
	v_add_f32_e32 v17, 1.0, v17
	v_add_f32_e32 v10, 1.0, v10
	v_add_f32_e32 v11, 1.0, v11
	v_add_f32_e32 v12, 1.0, v12
	v_add_f32_e32 v13, 1.0, v13
	v_rcp_f32_e32 v14, v14
	v_rcp_f32_e32 v15, v15
	v_rcp_f32_e32 v16, v16
	v_rcp_f32_e32 v17, v17
	v_rcp_f32_e32 v10, v10
	v_rcp_f32_e32 v11, v11
	v_rcp_f32_e32 v12, v12
	v_rcp_f32_e32 v13, v13
	s_waitcnt vmcnt(9)
	v_lshlrev_b32_e32 v146, 16, v234
	v_and_b32_e32 v147, 0xffff0000, v234
	v_lshlrev_b32_e32 v148, 16, v235
	v_and_b32_e32 v149, 0xffff0000, v235
	v_lshlrev_b32_e32 v150, 16, v236
	v_and_b32_e32 v151, 0xffff0000, v236
	v_lshlrev_b32_e32 v166, 16, v237
	v_and_b32_e32 v167, 0xffff0000, v237
	v_mul_f32_e32 v14, v14, v146
	v_mul_f32_e32 v15, v15, v147
	v_mul_f32_e32 v16, v16, v148
	v_mul_f32_e32 v17, v17, v149
	v_mul_f32_e32 v10, v10, v150
	v_mul_f32_e32 v11, v11, v151
	v_mul_f32_e32 v12, v12, v166
	v_mul_f32_e32 v13, v13, v167
	v_lshlrev_b32_e32 v146, 16, v238
	v_and_b32_e32 v147, 0xffff0000, v238
	v_lshlrev_b32_e32 v148, 16, v239
	v_and_b32_e32 v149, 0xffff0000, v239
	v_lshlrev_b32_e32 v150, 16, v240
	v_and_b32_e32 v151, 0xffff0000, v240
	v_lshlrev_b32_e32 v166, 16, v241
	v_and_b32_e32 v167, 0xffff0000, v241
	v_mul_f32_e32 v14, v14, v146
	v_mul_f32_e32 v15, v15, v147
	v_mul_f32_e32 v16, v16, v148
	v_mul_f32_e32 v17, v17, v149
	v_mul_f32_e32 v10, v10, v150
	v_mul_f32_e32 v11, v11, v151
	v_mul_f32_e32 v12, v12, v166
	v_mul_f32_e32 v13, v13, v167
	v_cvt_pk_bf16_f32 v138, v14, v15
	v_cvt_pk_bf16_f32 v139, v16, v17
	v_cvt_pk_bf16_f32 v140, v10, v11
	v_cvt_pk_bf16_f32 v141, v12, v13
	global_store_dwordx4 v[182:183], v[138:141], off offset:1280
	v_lshl_add_u64 v[182:183], v[182:183], 0, v[178:179]
	v_add_f32_e32 v6, v6, v170
	v_add_f32_e32 v7, v7, v171
	v_add_f32_e32 v8, v8, v172
	v_add_f32_e32 v9, v9, v173
	v_add_f32_e32 v2, v2, v174
	v_add_f32_e32 v3, v3, v175
	v_add_f32_e32 v4, v4, v176
	v_add_f32_e32 v5, v5, v177
	v_mul_f32_e32 v6, 0xbfb8aa3b, v6
	v_mul_f32_e32 v7, 0xbfb8aa3b, v7
	v_mul_f32_e32 v8, 0xbfb8aa3b, v8
	v_mul_f32_e32 v9, 0xbfb8aa3b, v9
	v_mul_f32_e32 v2, 0xbfb8aa3b, v2
	v_mul_f32_e32 v3, 0xbfb8aa3b, v3
	v_mul_f32_e32 v4, 0xbfb8aa3b, v4
	v_mul_f32_e32 v5, 0xbfb8aa3b, v5
	v_exp_f32_e32 v6, v6
	v_exp_f32_e32 v7, v7
	v_exp_f32_e32 v8, v8
	v_exp_f32_e32 v9, v9
	v_exp_f32_e32 v2, v2
	v_exp_f32_e32 v3, v3
	v_exp_f32_e32 v4, v4
	v_exp_f32_e32 v5, v5
	v_add_f32_e32 v6, 1.0, v6
	v_add_f32_e32 v7, 1.0, v7
	v_add_f32_e32 v8, 1.0, v8
	v_add_f32_e32 v9, 1.0, v9
	v_add_f32_e32 v2, 1.0, v2
	v_add_f32_e32 v3, 1.0, v3
	v_add_f32_e32 v4, 1.0, v4
	v_add_f32_e32 v5, 1.0, v5
	v_rcp_f32_e32 v6, v6
	v_rcp_f32_e32 v7, v7
	v_rcp_f32_e32 v8, v8
	v_rcp_f32_e32 v9, v9
	v_rcp_f32_e32 v2, v2
	v_rcp_f32_e32 v3, v3
	v_rcp_f32_e32 v4, v4
	v_rcp_f32_e32 v5, v5
	s_waitcnt vmcnt(7)
	v_lshlrev_b32_e32 v146, 16, v242
	v_and_b32_e32 v147, 0xffff0000, v242
	v_lshlrev_b32_e32 v148, 16, v243
	v_and_b32_e32 v149, 0xffff0000, v243
	v_lshlrev_b32_e32 v150, 16, v244
	v_and_b32_e32 v151, 0xffff0000, v244
	v_lshlrev_b32_e32 v166, 16, v245
	v_and_b32_e32 v167, 0xffff0000, v245
	v_mul_f32_e32 v6, v6, v146
	v_mul_f32_e32 v7, v7, v147
	v_mul_f32_e32 v8, v8, v148
	v_mul_f32_e32 v9, v9, v149
	v_mul_f32_e32 v2, v2, v150
	v_mul_f32_e32 v3, v3, v151
	v_mul_f32_e32 v4, v4, v166
	v_mul_f32_e32 v5, v5, v167
	v_lshlrev_b32_e32 v146, 16, v246
	v_and_b32_e32 v147, 0xffff0000, v246
	v_lshlrev_b32_e32 v148, 16, v247
	v_and_b32_e32 v149, 0xffff0000, v247
	v_lshlrev_b32_e32 v150, 16, v248
	v_and_b32_e32 v151, 0xffff0000, v248
	v_lshlrev_b32_e32 v166, 16, v249
	v_and_b32_e32 v167, 0xffff0000, v249
	v_mul_f32_e32 v6, v6, v146
	v_mul_f32_e32 v7, v7, v147
	v_mul_f32_e32 v8, v8, v148
	v_mul_f32_e32 v9, v9, v149
	v_mul_f32_e32 v2, v2, v150
	v_mul_f32_e32 v3, v3, v151
	v_mul_f32_e32 v4, v4, v166
	v_mul_f32_e32 v5, v5, v167
	v_cvt_pk_bf16_f32 v142, v6, v7
	v_cvt_pk_bf16_f32 v143, v8, v9
	v_cvt_pk_bf16_f32 v144, v2, v3
	v_cvt_pk_bf16_f32 v145, v4, v5
	global_store_dwordx4 v[182:183], v[142:145], off offset:1280
	s_cbranch_vccnz .LBB0_655
	s_andn2_b64 vcc, exec, s[4:5]
	s_cbranch_vccnz .LBB0_654
	s_barrier
	s_branch .LBB0_654
